# GEMM K-loops: hand-off overlap - the post-MFMA barrier moved 2 MFMAs earlier with the trailing MFMAs at s_setprio 2
# speedup vs baseline: 1.0194x; 1.0025x over previous
.Lk367_body:
	v_add_u32_e32 v154, s53, v144
	v_add_u32_e32 v170, s90, v144
	ds_read_b128 v[140:143], v154
	ds_read_b128 v[146:149], v154 offset:1024
	ds_read_b128 v[150:153], v154 offset:2048
	ds_read_b128 v[154:157], v154 offset:3072
	ds_read_b128 v[158:161], v170
	ds_read_b128 v[162:165], v170 offset:1024
	ds_read_b128 v[166:169], v170 offset:2048
	ds_read_b128 v[170:173], v170 offset:3072
	s_add_u32 s96, s4, 0xfff00000
	s_addc_u32 s97, s5, -1
	s_mov_b32 m0, s51
	s_nop 0
	global_load_lds_dwordx4 v128, s[96:97]
	s_mov_b32 m0, s52
	s_nop 0
	global_load_lds_dwordx4 v132, s[96:97]
	s_add_i32 m0, s49, 0xc000
	ds_read_b128 v[188:191], v145
	ds_read_b128 v[192:195], v145 offset:1024
	ds_read_b128 v[196:199], v145 offset:2048
	ds_read_b128 v[200:203], v145 offset:3072
	ds_read_b128 v[204:207], v145 offset:4096
	ds_read_b128 v[208:211], v145 offset:5120
	ds_read_b128 v[212:215], v145 offset:6144
	ds_read_b128 v[216:219], v145 offset:7168
	global_load_lds_dwordx4 v136, s[4:5]
	s_add_i32 m0, s49, 0xe000
	s_nop 0
	global_load_lds_dwordx4 v138, s[4:5]
	s_waitcnt vmcnt(8)
	s_waitcnt lgkmcnt(0)
	s_barrier
	s_setprio 1
	s_waitcnt lgkmcnt(0)
	v_mfma_f32_16x16x32_bf16 v[124:127], v[140:143], v[188:191], v[124:127]
	v_mfma_f32_16x16x32_bf16 v[120:123], v[150:153], v[188:191], v[120:123]
	v_mfma_f32_16x16x32_bf16 v[108:111], v[140:143], v[196:199], v[108:111]
	v_mfma_f32_16x16x32_bf16 v[104:107], v[150:153], v[196:199], v[104:107]
	v_mfma_f32_16x16x32_bf16 v[92:95], v[140:143], v[204:207], v[92:95]
	v_mfma_f32_16x16x32_bf16 v[88:91], v[150:153], v[204:207], v[88:91]
	v_mfma_f32_16x16x32_bf16 v[76:79], v[140:143], v[212:215], v[76:79]
	v_mfma_f32_16x16x32_bf16 v[72:75], v[150:153], v[212:215], v[72:75]
	v_mfma_f32_16x16x32_bf16 v[124:127], v[146:149], v[192:195], v[124:127]
	v_mfma_f32_16x16x32_bf16 v[120:123], v[154:157], v[192:195], v[120:123]
	v_mfma_f32_16x16x32_bf16 v[108:111], v[146:149], v[200:203], v[108:111]
	v_mfma_f32_16x16x32_bf16 v[104:107], v[154:157], v[200:203], v[104:107]
	v_mfma_f32_16x16x32_bf16 v[92:95], v[146:149], v[208:211], v[92:95]
	v_mfma_f32_16x16x32_bf16 v[88:91], v[154:157], v[208:211], v[88:91]
	v_mfma_f32_16x16x32_bf16 v[76:79], v[146:149], v[216:219], v[76:79]
	v_mfma_f32_16x16x32_bf16 v[72:75], v[154:157], v[216:219], v[72:75]
	s_setprio 0
	s_setprio 1
	v_mfma_f32_16x16x32_bf16 v[116:119], v[158:161], v[188:191], v[116:119]
	v_mfma_f32_16x16x32_bf16 v[112:115], v[166:169], v[188:191], v[112:115]
	v_mfma_f32_16x16x32_bf16 v[100:103], v[158:161], v[196:199], v[100:103]
	v_mfma_f32_16x16x32_bf16 v[96:99], v[166:169], v[196:199], v[96:99]
	v_mfma_f32_16x16x32_bf16 v[84:87], v[158:161], v[204:207], v[84:87]
	v_mfma_f32_16x16x32_bf16 v[80:83], v[166:169], v[204:207], v[80:83]
	v_mfma_f32_16x16x32_bf16 v[68:71], v[158:161], v[212:215], v[68:71]
	v_mfma_f32_16x16x32_bf16 v[64:67], v[166:169], v[212:215], v[64:67]
	v_mfma_f32_16x16x32_bf16 v[116:119], v[162:165], v[192:195], v[116:119]
	v_mfma_f32_16x16x32_bf16 v[112:115], v[170:173], v[192:195], v[112:115]
	v_mfma_f32_16x16x32_bf16 v[100:103], v[162:165], v[200:203], v[100:103]
	v_mfma_f32_16x16x32_bf16 v[96:99], v[170:173], v[200:203], v[96:99]
	v_mfma_f32_16x16x32_bf16 v[84:87], v[162:165], v[208:211], v[84:87]
	v_mfma_f32_16x16x32_bf16 v[80:83], v[170:173], v[208:211], v[80:83]
	s_setprio 2
	s_barrier
	v_mfma_f32_16x16x32_bf16 v[68:71], v[162:165], v[216:219], v[68:71]
	v_mfma_f32_16x16x32_bf16 v[64:67], v[170:173], v[216:219], v[64:67]
	s_setprio 0
	s_add_i32 s53, s53, s43
	s_add_u32 s38, s6, 0x80
	s_addc_u32 s39, s7, 0
	s_mov_b32 m0, s53
	ds_read_b128 v[188:191], v145 offset:16384
	ds_read_b128 v[192:195], v145 offset:17408
	ds_read_b128 v[196:199], v145 offset:18432
	ds_read_b128 v[200:203], v145 offset:19456
	ds_read_b128 v[204:207], v145 offset:20480
	ds_read_b128 v[208:211], v145 offset:21504
	ds_read_b128 v[212:215], v145 offset:22528
	ds_read_b128 v[216:219], v145 offset:23552
	global_load_lds_dwordx4 v130, s[6:7]
	s_add_i32 m0, s53, 0x2000
	s_add_u32 s80, s6, 0x100000
	s_addc_u32 s81, s7, 0
	s_add_i32 s53, s90, s43
	global_load_lds_dwordx4 v134, s[6:7]
	s_mov_b32 m0, s53
	s_nop 0
	global_load_lds_dwordx4 v130, s[80:81]
	s_add_i32 m0, s53, 0x2000
	s_nop 0
	global_load_lds_dwordx4 v134, s[80:81]
	s_waitcnt vmcnt(6)
	s_waitcnt lgkmcnt(0)
	s_barrier
	s_setprio 1
	s_waitcnt lgkmcnt(0)
	v_mfma_f32_16x16x32_bf16 v[60:63], v[140:143], v[188:191], v[60:63]
	v_mfma_f32_16x16x32_bf16 v[56:59], v[150:153], v[188:191], v[56:59]
	v_mfma_f32_16x16x32_bf16 v[44:47], v[140:143], v[196:199], v[44:47]
	v_mfma_f32_16x16x32_bf16 v[40:43], v[150:153], v[196:199], v[40:43]
	v_mfma_f32_16x16x32_bf16 v[28:31], v[140:143], v[204:207], v[28:31]
	v_mfma_f32_16x16x32_bf16 v[24:27], v[150:153], v[204:207], v[24:27]
	v_mfma_f32_16x16x32_bf16 v[12:15], v[140:143], v[212:215], v[12:15]
	v_mfma_f32_16x16x32_bf16 v[8:11], v[150:153], v[212:215], v[8:11]
	v_mfma_f32_16x16x32_bf16 v[60:63], v[146:149], v[192:195], v[60:63]
	v_mfma_f32_16x16x32_bf16 v[56:59], v[154:157], v[192:195], v[56:59]
	v_mfma_f32_16x16x32_bf16 v[44:47], v[146:149], v[200:203], v[44:47]
	v_mfma_f32_16x16x32_bf16 v[40:43], v[154:157], v[200:203], v[40:43]
	v_mfma_f32_16x16x32_bf16 v[28:31], v[146:149], v[208:211], v[28:31]
	v_mfma_f32_16x16x32_bf16 v[24:27], v[154:157], v[208:211], v[24:27]
	v_mfma_f32_16x16x32_bf16 v[12:15], v[146:149], v[216:219], v[12:15]
	v_mfma_f32_16x16x32_bf16 v[8:11], v[154:157], v[216:219], v[8:11]
	s_setprio 0
	s_setprio 1
	v_mfma_f32_16x16x32_bf16 v[52:55], v[158:161], v[188:191], v[52:55]
	v_mfma_f32_16x16x32_bf16 v[48:51], v[166:169], v[188:191], v[48:51]
	v_mfma_f32_16x16x32_bf16 v[36:39], v[158:161], v[196:199], v[36:39]
	v_mfma_f32_16x16x32_bf16 v[32:35], v[166:169], v[196:199], v[32:35]
	v_mfma_f32_16x16x32_bf16 v[20:23], v[158:161], v[204:207], v[20:23]
	v_mfma_f32_16x16x32_bf16 v[16:19], v[166:169], v[204:207], v[16:19]
	v_mfma_f32_16x16x32_bf16 v[4:7], v[158:161], v[212:215], v[4:7]
	v_mfma_f32_16x16x32_bf16 v[0:3], v[166:169], v[212:215], v[0:3]
	v_mfma_f32_16x16x32_bf16 v[52:55], v[162:165], v[192:195], v[52:55]
	v_mfma_f32_16x16x32_bf16 v[48:51], v[170:173], v[192:195], v[48:51]
	v_mfma_f32_16x16x32_bf16 v[36:39], v[162:165], v[200:203], v[36:39]
	v_mfma_f32_16x16x32_bf16 v[32:35], v[170:173], v[200:203], v[32:35]
	v_mfma_f32_16x16x32_bf16 v[20:23], v[162:165], v[208:211], v[20:23]
	v_mfma_f32_16x16x32_bf16 v[16:19], v[170:173], v[208:211], v[16:19]
	s_setprio 2
	s_barrier
	v_mfma_f32_16x16x32_bf16 v[4:7], v[162:165], v[216:219], v[4:7]
	v_mfma_f32_16x16x32_bf16 v[0:3], v[170:173], v[216:219], v[0:3]
	s_setprio 0
	s_add_i32 s53, 0, 0x18000
	s_add_i32 s80, 0, 0x1c000
	v_add_u32_e32 v154, s53, v144
	v_add_u32_e32 v170, s80, v144
	ds_read_b128 v[140:143], v154
	ds_read_b128 v[146:149], v154 offset:1024
	ds_read_b128 v[150:153], v154 offset:2048
	ds_read_b128 v[154:157], v154 offset:3072
	ds_read_b128 v[158:161], v170
	ds_read_b128 v[162:165], v170 offset:1024
	ds_read_b128 v[166:169], v170 offset:2048
	ds_read_b128 v[170:173], v170 offset:3072
	s_mov_b32 m0, s49
	s_nop 0
	global_load_lds_dwordx4 v128, s[30:31]
	s_mov_b32 m0, s15
	s_nop 0
	global_load_lds_dwordx4 v132, s[30:31]
	s_add_u32 s30, s30, 0x100000
	s_addc_u32 s31, s31, 0
	s_mov_b32 m0, s36
	ds_read_b128 v[188:191], v145 offset:32768
	ds_read_b128 v[192:195], v145 offset:33792
	ds_read_b128 v[196:199], v145 offset:34816
	ds_read_b128 v[200:203], v145 offset:35840
	ds_read_b128 v[204:207], v145 offset:36864
	ds_read_b128 v[208:211], v145 offset:37888
	ds_read_b128 v[212:215], v145 offset:38912
	ds_read_b128 v[216:219], v145 offset:39936
	global_load_lds_dwordx4 v128, s[30:31]
	s_mov_b32 m0, s50
	s_nop 0
	global_load_lds_dwordx4 v132, s[30:31]
	s_waitcnt vmcnt(8)
	s_waitcnt lgkmcnt(0)
	s_barrier
	s_setprio 1
	s_waitcnt lgkmcnt(0)
	v_mfma_f32_16x16x32_bf16 v[124:127], v[140:143], v[188:191], v[124:127]
	v_mfma_f32_16x16x32_bf16 v[120:123], v[150:153], v[188:191], v[120:123]
	v_mfma_f32_16x16x32_bf16 v[108:111], v[140:143], v[196:199], v[108:111]
	v_mfma_f32_16x16x32_bf16 v[104:107], v[150:153], v[196:199], v[104:107]
	v_mfma_f32_16x16x32_bf16 v[92:95], v[140:143], v[204:207], v[92:95]
	v_mfma_f32_16x16x32_bf16 v[88:91], v[150:153], v[204:207], v[88:91]
	v_mfma_f32_16x16x32_bf16 v[76:79], v[140:143], v[212:215], v[76:79]
	v_mfma_f32_16x16x32_bf16 v[72:75], v[150:153], v[212:215], v[72:75]
	v_mfma_f32_16x16x32_bf16 v[124:127], v[146:149], v[192:195], v[124:127]
	v_mfma_f32_16x16x32_bf16 v[120:123], v[154:157], v[192:195], v[120:123]
	v_mfma_f32_16x16x32_bf16 v[108:111], v[146:149], v[200:203], v[108:111]
	v_mfma_f32_16x16x32_bf16 v[104:107], v[154:157], v[200:203], v[104:107]
	v_mfma_f32_16x16x32_bf16 v[92:95], v[146:149], v[208:211], v[92:95]
	v_mfma_f32_16x16x32_bf16 v[88:91], v[154:157], v[208:211], v[88:91]
	v_mfma_f32_16x16x32_bf16 v[76:79], v[146:149], v[216:219], v[76:79]
	v_mfma_f32_16x16x32_bf16 v[72:75], v[154:157], v[216:219], v[72:75]
	s_setprio 0
	s_setprio 1
	v_mfma_f32_16x16x32_bf16 v[116:119], v[158:161], v[188:191], v[116:119]
	v_mfma_f32_16x16x32_bf16 v[112:115], v[166:169], v[188:191], v[112:115]
	v_mfma_f32_16x16x32_bf16 v[100:103], v[158:161], v[196:199], v[100:103]
	v_mfma_f32_16x16x32_bf16 v[96:99], v[166:169], v[196:199], v[96:99]
	v_mfma_f32_16x16x32_bf16 v[84:87], v[158:161], v[204:207], v[84:87]
	v_mfma_f32_16x16x32_bf16 v[80:83], v[166:169], v[204:207], v[80:83]
	v_mfma_f32_16x16x32_bf16 v[68:71], v[158:161], v[212:215], v[68:71]
	v_mfma_f32_16x16x32_bf16 v[64:67], v[166:169], v[212:215], v[64:67]
	v_mfma_f32_16x16x32_bf16 v[116:119], v[162:165], v[192:195], v[116:119]
	v_mfma_f32_16x16x32_bf16 v[112:115], v[170:173], v[192:195], v[112:115]
	v_mfma_f32_16x16x32_bf16 v[100:103], v[162:165], v[200:203], v[100:103]
	v_mfma_f32_16x16x32_bf16 v[96:99], v[170:173], v[200:203], v[96:99]
	v_mfma_f32_16x16x32_bf16 v[84:87], v[162:165], v[208:211], v[84:87]
	v_mfma_f32_16x16x32_bf16 v[80:83], v[170:173], v[208:211], v[80:83]
	s_setprio 2
	s_barrier
	v_mfma_f32_16x16x32_bf16 v[68:71], v[162:165], v[216:219], v[68:71]
	v_mfma_f32_16x16x32_bf16 v[64:67], v[170:173], v[216:219], v[64:67]
	s_setprio 0
	s_add_i32 s30, s53, s43
	s_mov_b32 m0, s30
	ds_read_b128 v[188:191], v145 offset:49152
	ds_read_b128 v[192:195], v145 offset:50176
	ds_read_b128 v[196:199], v145 offset:51200
	ds_read_b128 v[200:203], v145 offset:52224
	ds_read_b128 v[204:207], v145 offset:53248
	ds_read_b128 v[208:211], v145 offset:54272
	ds_read_b128 v[212:215], v145 offset:55296
	ds_read_b128 v[216:219], v145 offset:56320
	global_load_lds_dwordx4 v130, s[38:39]
	s_add_i32 m0, s30, 0x2000
	s_add_u32 s6, s6, 0x100080
	s_addc_u32 s7, s7, 0
	s_add_i32 s30, s80, s43
	global_load_lds_dwordx4 v134, s[38:39]
	s_mov_b32 m0, s30
	s_nop 0
	global_load_lds_dwordx4 v130, s[6:7]
	s_add_i32 m0, s30, 0x2000
	s_nop 0
	global_load_lds_dwordx4 v134, s[6:7]
	s_waitcnt vmcnt(6)
	s_waitcnt lgkmcnt(0)
	s_barrier
	s_setprio 1
	s_waitcnt lgkmcnt(0)
	v_mfma_f32_16x16x32_bf16 v[60:63], v[140:143], v[188:191], v[60:63]
	v_mfma_f32_16x16x32_bf16 v[56:59], v[150:153], v[188:191], v[56:59]
	v_mfma_f32_16x16x32_bf16 v[44:47], v[140:143], v[196:199], v[44:47]
	s_add_i32 s79, s79, 2
	v_mfma_f32_16x16x32_bf16 v[40:43], v[150:153], v[196:199], v[40:43]
	v_mfma_f32_16x16x32_bf16 v[28:31], v[140:143], v[204:207], v[28:31]
	v_mfma_f32_16x16x32_bf16 v[24:27], v[150:153], v[204:207], v[24:27]
	s_add_u32 s4, s4, 0x100
	s_addc_u32 s5, s5, 0
	v_mfma_f32_16x16x32_bf16 v[12:15], v[140:143], v[212:215], v[12:15]
	v_mfma_f32_16x16x32_bf16 v[8:11], v[150:153], v[212:215], v[8:11]
	v_mfma_f32_16x16x32_bf16 v[60:63], v[146:149], v[192:195], v[60:63]
	s_add_u32 s55, s55, 0x100
	s_addc_u32 s78, s78, 0
	v_mfma_f32_16x16x32_bf16 v[56:59], v[154:157], v[192:195], v[56:59]
	v_mfma_f32_16x16x32_bf16 v[44:47], v[146:149], v[200:203], v[44:47]
	v_mfma_f32_16x16x32_bf16 v[40:43], v[154:157], v[200:203], v[40:43]
	s_add_u32 s6, s4, 0xfff00080
	s_addc_u32 s7, s5, -1
	v_mfma_f32_16x16x32_bf16 v[28:31], v[146:149], v[208:211], v[28:31]
	v_mfma_f32_16x16x32_bf16 v[24:27], v[154:157], v[208:211], v[24:27]
	v_mfma_f32_16x16x32_bf16 v[12:15], v[146:149], v[216:219], v[12:15]
	s_add_i32 s53, 0, 0x10000
	v_mfma_f32_16x16x32_bf16 v[8:11], v[154:157], v[216:219], v[8:11]
	s_setprio 0
	s_setprio 1
	v_mfma_f32_16x16x32_bf16 v[52:55], v[158:161], v[188:191], v[52:55]
	v_mfma_f32_16x16x32_bf16 v[48:51], v[166:169], v[188:191], v[48:51]
	s_cmp_eq_u32 s79, 60
	s_cselect_b32 s31, s27, s7
	s_cselect_b32 s30, s26, s6
	s_cselect_b32 s7, s29, s78
	s_cselect_b32 s6, s28, s55
	v_mfma_f32_16x16x32_bf16 v[36:39], v[158:161], v[196:199], v[36:39]
	v_mfma_f32_16x16x32_bf16 v[32:35], v[166:169], v[196:199], v[32:35]
	v_mfma_f32_16x16x32_bf16 v[20:23], v[158:161], v[204:207], v[20:23]
	s_add_i32 s90, 0, 0x14000
	v_mfma_f32_16x16x32_bf16 v[16:19], v[166:169], v[204:207], v[16:19]
	v_mfma_f32_16x16x32_bf16 v[4:7], v[158:161], v[212:215], v[4:7]
	v_mfma_f32_16x16x32_bf16 v[0:3], v[166:169], v[212:215], v[0:3]
	s_cmp_gt_u32 s79, 61
	v_mfma_f32_16x16x32_bf16 v[52:55], v[162:165], v[192:195], v[52:55]
	v_mfma_f32_16x16x32_bf16 v[48:51], v[170:173], v[192:195], v[48:51]
	v_mfma_f32_16x16x32_bf16 v[36:39], v[162:165], v[200:203], v[36:39]
	v_mfma_f32_16x16x32_bf16 v[32:35], v[170:173], v[200:203], v[32:35]
	v_mfma_f32_16x16x32_bf16 v[20:23], v[162:165], v[208:211], v[20:23]
	v_mfma_f32_16x16x32_bf16 v[16:19], v[170:173], v[208:211], v[16:19]
	s_setprio 2
	s_barrier
	v_mfma_f32_16x16x32_bf16 v[4:7], v[162:165], v[216:219], v[4:7]
	v_mfma_f32_16x16x32_bf16 v[0:3], v[170:173], v[216:219], v[0:3]
	s_setprio 0
	s_cbranch_scc0 .Lk367_body
	s_and_b64 vcc, exec, s[24:25]
	s_cbranch_vccz .LBB0_370
	s_barrier

.LBB0_687:
	s_add_u32 s26, s24, 0xffe00080
	s_addc_u32 s27, s25, -1
	s_add_i32 s53, 0, 0x10000
	s_cmp_eq_u32 s79, 60
	s_cselect_b32 s29, s7, s27
	s_cselect_b32 s28, s6, s26
	s_cselect_b32 s27, s19, s78
	s_cselect_b32 s26, s18, s57
	s_add_i32 s85, 0, 0x14000
	v_add_u32_e32 v152, s53, v142
	v_add_u32_e32 v168, s85, v142
	ds_read_b128 v[138:141], v152
	ds_read_b128 v[144:147], v152 offset:1024
	ds_read_b128 v[148:151], v152 offset:2048
	ds_read_b128 v[152:155], v152 offset:3072
	ds_read_b128 v[156:159], v168
	ds_read_b128 v[160:163], v168 offset:1024
	ds_read_b128 v[164:167], v168 offset:2048
	ds_read_b128 v[168:171], v168 offset:3072
	s_add_u32 s98, s24, 0xffe00000
	s_addc_u32 s99, s25, -1
	s_mov_b32 m0, s44
	s_nop 0
	global_load_lds_dwordx4 v132, s[98:99]
	s_mov_b32 m0, s48
	s_nop 0
	global_load_lds_dwordx4 v130, s[98:99]
	s_add_i32 m0, s31, 0xc000
	ds_read_b128 v[172:175], v143
	ds_read_b128 v[188:191], v143 offset:1024
	ds_read_b128 v[192:195], v143 offset:2048
	ds_read_b128 v[196:199], v143 offset:3072
	ds_read_b128 v[200:203], v143 offset:4096
	ds_read_b128 v[204:207], v143 offset:5120
	ds_read_b128 v[208:211], v143 offset:6144
	ds_read_b128 v[212:215], v143 offset:7168
	global_load_lds_dwordx4 v134, s[24:25]
	s_add_i32 m0, s31, 0xe000
	s_nop 0
	global_load_lds_dwordx4 v136, s[24:25]
	s_waitcnt vmcnt(8)
	s_waitcnt lgkmcnt(0)
	s_barrier
	s_setprio 1
	s_waitcnt lgkmcnt(0)
	v_mfma_f32_16x16x32_bf16 v[124:127], v[138:141], v[172:175], v[124:127]
	v_mfma_f32_16x16x32_bf16 v[120:123], v[148:151], v[172:175], v[120:123]
	v_mfma_f32_16x16x32_bf16 v[108:111], v[138:141], v[192:195], v[108:111]
	v_mfma_f32_16x16x32_bf16 v[104:107], v[148:151], v[192:195], v[104:107]
	v_mfma_f32_16x16x32_bf16 v[92:95], v[138:141], v[200:203], v[92:95]
	v_mfma_f32_16x16x32_bf16 v[88:91], v[148:151], v[200:203], v[88:91]
	v_mfma_f32_16x16x32_bf16 v[76:79], v[138:141], v[208:211], v[76:79]
	v_mfma_f32_16x16x32_bf16 v[72:75], v[148:151], v[208:211], v[72:75]
	v_mfma_f32_16x16x32_bf16 v[124:127], v[144:147], v[188:191], v[124:127]
	v_mfma_f32_16x16x32_bf16 v[120:123], v[152:155], v[188:191], v[120:123]
	v_mfma_f32_16x16x32_bf16 v[108:111], v[144:147], v[196:199], v[108:111]
	v_mfma_f32_16x16x32_bf16 v[104:107], v[152:155], v[196:199], v[104:107]
	v_mfma_f32_16x16x32_bf16 v[92:95], v[144:147], v[204:207], v[92:95]
	v_mfma_f32_16x16x32_bf16 v[88:91], v[152:155], v[204:207], v[88:91]
	v_mfma_f32_16x16x32_bf16 v[76:79], v[144:147], v[212:215], v[76:79]
	v_mfma_f32_16x16x32_bf16 v[72:75], v[152:155], v[212:215], v[72:75]
	s_setprio 0
	s_setprio 1
	v_mfma_f32_16x16x32_bf16 v[116:119], v[156:159], v[172:175], v[116:119]
	v_mfma_f32_16x16x32_bf16 v[112:115], v[164:167], v[172:175], v[112:115]
	v_mfma_f32_16x16x32_bf16 v[100:103], v[156:159], v[192:195], v[100:103]
	v_mfma_f32_16x16x32_bf16 v[96:99], v[164:167], v[192:195], v[96:99]
	v_mfma_f32_16x16x32_bf16 v[84:87], v[156:159], v[200:203], v[84:87]
	v_mfma_f32_16x16x32_bf16 v[80:83], v[164:167], v[200:203], v[80:83]
	v_mfma_f32_16x16x32_bf16 v[68:71], v[156:159], v[208:211], v[68:71]
	v_mfma_f32_16x16x32_bf16 v[64:67], v[164:167], v[208:211], v[64:67]
	v_mfma_f32_16x16x32_bf16 v[116:119], v[160:163], v[188:191], v[116:119]
	v_mfma_f32_16x16x32_bf16 v[112:115], v[168:171], v[188:191], v[112:115]
	v_mfma_f32_16x16x32_bf16 v[100:103], v[160:163], v[196:199], v[100:103]
	v_mfma_f32_16x16x32_bf16 v[96:99], v[168:171], v[196:199], v[96:99]
	v_mfma_f32_16x16x32_bf16 v[84:87], v[160:163], v[204:207], v[84:87]
	v_mfma_f32_16x16x32_bf16 v[80:83], v[168:171], v[204:207], v[80:83]
	s_setprio 2
	s_barrier
	v_mfma_f32_16x16x32_bf16 v[68:71], v[160:163], v[212:215], v[68:71]
	v_mfma_f32_16x16x32_bf16 v[64:67], v[168:171], v[212:215], v[64:67]
	s_setprio 0
	s_add_i32 s53, s53, s30
	s_add_u32 s90, s26, 0x80
	s_addc_u32 s91, s27, 0
	s_mov_b32 m0, s53
	ds_read_b128 v[172:175], v143 offset:16384
	ds_read_b128 v[188:191], v143 offset:17408
	ds_read_b128 v[192:195], v143 offset:18432
	ds_read_b128 v[196:199], v143 offset:19456
	ds_read_b128 v[200:203], v143 offset:20480
	ds_read_b128 v[204:207], v143 offset:21504
	ds_read_b128 v[208:211], v143 offset:22528
	ds_read_b128 v[212:215], v143 offset:23552
	global_load_lds_dwordx4 v176, s[26:27]
	s_add_i32 m0, s53, 0x2000
	s_add_u32 s80, s26, 0x100000
	s_addc_u32 s81, s27, 0
	s_add_i32 s53, s85, s30
	global_load_lds_dwordx4 v128, s[26:27]
	s_mov_b32 m0, s53
	s_nop 0
	global_load_lds_dwordx4 v176, s[80:81]
	s_add_i32 m0, s53, 0x2000
	s_nop 0
	global_load_lds_dwordx4 v128, s[80:81]
	s_waitcnt vmcnt(6)
	s_waitcnt lgkmcnt(0)
	s_barrier
	s_setprio 1
	s_waitcnt lgkmcnt(0)
	v_mfma_f32_16x16x32_bf16 v[60:63], v[138:141], v[172:175], v[60:63]
	v_mfma_f32_16x16x32_bf16 v[56:59], v[148:151], v[172:175], v[56:59]
	v_mfma_f32_16x16x32_bf16 v[44:47], v[138:141], v[192:195], v[44:47]
	v_mfma_f32_16x16x32_bf16 v[40:43], v[148:151], v[192:195], v[40:43]
	v_mfma_f32_16x16x32_bf16 v[28:31], v[138:141], v[200:203], v[28:31]
	v_mfma_f32_16x16x32_bf16 v[24:27], v[148:151], v[200:203], v[24:27]
	v_mfma_f32_16x16x32_bf16 v[12:15], v[138:141], v[208:211], v[12:15]
	v_mfma_f32_16x16x32_bf16 v[8:11], v[148:151], v[208:211], v[8:11]
	v_mfma_f32_16x16x32_bf16 v[60:63], v[144:147], v[188:191], v[60:63]
	v_mfma_f32_16x16x32_bf16 v[56:59], v[152:155], v[188:191], v[56:59]
	v_mfma_f32_16x16x32_bf16 v[44:47], v[144:147], v[196:199], v[44:47]
	v_mfma_f32_16x16x32_bf16 v[40:43], v[152:155], v[196:199], v[40:43]
	v_mfma_f32_16x16x32_bf16 v[28:31], v[144:147], v[204:207], v[28:31]
	v_mfma_f32_16x16x32_bf16 v[24:27], v[152:155], v[204:207], v[24:27]
	v_mfma_f32_16x16x32_bf16 v[12:15], v[144:147], v[212:215], v[12:15]
	v_mfma_f32_16x16x32_bf16 v[8:11], v[152:155], v[212:215], v[8:11]
	s_setprio 0
	s_setprio 1
	v_mfma_f32_16x16x32_bf16 v[52:55], v[156:159], v[172:175], v[52:55]
	v_mfma_f32_16x16x32_bf16 v[48:51], v[164:167], v[172:175], v[48:51]
	v_mfma_f32_16x16x32_bf16 v[36:39], v[156:159], v[192:195], v[36:39]
	v_mfma_f32_16x16x32_bf16 v[32:35], v[164:167], v[192:195], v[32:35]
	v_mfma_f32_16x16x32_bf16 v[20:23], v[156:159], v[200:203], v[20:23]
	v_mfma_f32_16x16x32_bf16 v[16:19], v[164:167], v[200:203], v[16:19]
	v_mfma_f32_16x16x32_bf16 v[4:7], v[156:159], v[208:211], v[4:7]
	v_mfma_f32_16x16x32_bf16 v[0:3], v[164:167], v[208:211], v[0:3]
	v_mfma_f32_16x16x32_bf16 v[52:55], v[160:163], v[188:191], v[52:55]
	v_mfma_f32_16x16x32_bf16 v[48:51], v[168:171], v[188:191], v[48:51]
	v_mfma_f32_16x16x32_bf16 v[36:39], v[160:163], v[196:199], v[36:39]
	v_mfma_f32_16x16x32_bf16 v[32:35], v[168:171], v[196:199], v[32:35]
	v_mfma_f32_16x16x32_bf16 v[20:23], v[160:163], v[204:207], v[20:23]
	v_mfma_f32_16x16x32_bf16 v[16:19], v[168:171], v[204:207], v[16:19]
	s_setprio 2
	s_barrier
	v_mfma_f32_16x16x32_bf16 v[4:7], v[160:163], v[212:215], v[4:7]
	v_mfma_f32_16x16x32_bf16 v[0:3], v[168:171], v[212:215], v[0:3]
	s_setprio 0
	s_add_i32 s53, 0, 0x18000
	s_add_i32 s80, 0, 0x1c000
	v_add_u32_e32 v152, s53, v142
	v_add_u32_e32 v168, s80, v142
	ds_read_b128 v[138:141], v152
	ds_read_b128 v[144:147], v152 offset:1024
	ds_read_b128 v[148:151], v152 offset:2048
	ds_read_b128 v[152:155], v152 offset:3072
	ds_read_b128 v[156:159], v168
	ds_read_b128 v[160:163], v168 offset:1024
	ds_read_b128 v[164:167], v168 offset:2048
	ds_read_b128 v[168:171], v168 offset:3072
	s_mov_b32 m0, s31
	s_nop 0
	global_load_lds_dwordx4 v132, s[28:29]
	s_mov_b32 m0, s34
	s_nop 0
	global_load_lds_dwordx4 v130, s[28:29]
	s_add_u32 s28, s28, 0x200000
	s_addc_u32 s29, s29, 0
	s_mov_b32 m0, s35
	ds_read_b128 v[172:175], v143 offset:32768
	ds_read_b128 v[188:191], v143 offset:33792
	ds_read_b128 v[192:195], v143 offset:34816
	ds_read_b128 v[196:199], v143 offset:35840
	ds_read_b128 v[200:203], v143 offset:36864
	ds_read_b128 v[204:207], v143 offset:37888
	ds_read_b128 v[208:211], v143 offset:38912
	ds_read_b128 v[212:215], v143 offset:39936
	global_load_lds_dwordx4 v132, s[28:29]
	s_mov_b32 m0, s36
	s_nop 0
	global_load_lds_dwordx4 v130, s[28:29]
	s_waitcnt vmcnt(8)
	s_waitcnt lgkmcnt(0)
	s_barrier
	s_setprio 1
	s_waitcnt lgkmcnt(0)
	v_mfma_f32_16x16x32_bf16 v[124:127], v[138:141], v[172:175], v[124:127]
	v_mfma_f32_16x16x32_bf16 v[120:123], v[148:151], v[172:175], v[120:123]
	v_mfma_f32_16x16x32_bf16 v[108:111], v[138:141], v[192:195], v[108:111]
	v_mfma_f32_16x16x32_bf16 v[104:107], v[148:151], v[192:195], v[104:107]
	v_mfma_f32_16x16x32_bf16 v[92:95], v[138:141], v[200:203], v[92:95]
	v_mfma_f32_16x16x32_bf16 v[88:91], v[148:151], v[200:203], v[88:91]
	v_mfma_f32_16x16x32_bf16 v[76:79], v[138:141], v[208:211], v[76:79]
	v_mfma_f32_16x16x32_bf16 v[72:75], v[148:151], v[208:211], v[72:75]
	v_mfma_f32_16x16x32_bf16 v[124:127], v[144:147], v[188:191], v[124:127]
	v_mfma_f32_16x16x32_bf16 v[120:123], v[152:155], v[188:191], v[120:123]
	v_mfma_f32_16x16x32_bf16 v[108:111], v[144:147], v[196:199], v[108:111]
	v_mfma_f32_16x16x32_bf16 v[104:107], v[152:155], v[196:199], v[104:107]
	v_mfma_f32_16x16x32_bf16 v[92:95], v[144:147], v[204:207], v[92:95]
	v_mfma_f32_16x16x32_bf16 v[88:91], v[152:155], v[204:207], v[88:91]
	v_mfma_f32_16x16x32_bf16 v[76:79], v[144:147], v[212:215], v[76:79]
	v_mfma_f32_16x16x32_bf16 v[72:75], v[152:155], v[212:215], v[72:75]
	s_setprio 0
	s_setprio 1
	v_mfma_f32_16x16x32_bf16 v[116:119], v[156:159], v[172:175], v[116:119]
	v_mfma_f32_16x16x32_bf16 v[112:115], v[164:167], v[172:175], v[112:115]
	v_mfma_f32_16x16x32_bf16 v[100:103], v[156:159], v[192:195], v[100:103]
	v_mfma_f32_16x16x32_bf16 v[96:99], v[164:167], v[192:195], v[96:99]
	v_mfma_f32_16x16x32_bf16 v[84:87], v[156:159], v[200:203], v[84:87]
	v_mfma_f32_16x16x32_bf16 v[80:83], v[164:167], v[200:203], v[80:83]
	v_mfma_f32_16x16x32_bf16 v[68:71], v[156:159], v[208:211], v[68:71]
	v_mfma_f32_16x16x32_bf16 v[64:67], v[164:167], v[208:211], v[64:67]
	v_mfma_f32_16x16x32_bf16 v[116:119], v[160:163], v[188:191], v[116:119]
	v_mfma_f32_16x16x32_bf16 v[112:115], v[168:171], v[188:191], v[112:115]
	v_mfma_f32_16x16x32_bf16 v[100:103], v[160:163], v[196:199], v[100:103]
	v_mfma_f32_16x16x32_bf16 v[96:99], v[168:171], v[196:199], v[96:99]
	v_mfma_f32_16x16x32_bf16 v[84:87], v[160:163], v[204:207], v[84:87]
	v_mfma_f32_16x16x32_bf16 v[80:83], v[168:171], v[204:207], v[80:83]
	s_setprio 2
	s_barrier
	v_mfma_f32_16x16x32_bf16 v[68:71], v[160:163], v[212:215], v[68:71]
	v_mfma_f32_16x16x32_bf16 v[64:67], v[168:171], v[212:215], v[64:67]
	s_setprio 0
	s_add_i32 s28, s53, s30
	s_mov_b32 m0, s28
	ds_read_b128 v[172:175], v143 offset:49152
	ds_read_b128 v[188:191], v143 offset:50176
	ds_read_b128 v[192:195], v143 offset:51200
	ds_read_b128 v[196:199], v143 offset:52224
	ds_read_b128 v[200:203], v143 offset:53248
	ds_read_b128 v[204:207], v143 offset:54272
	ds_read_b128 v[208:211], v143 offset:55296
	ds_read_b128 v[212:215], v143 offset:56320
	global_load_lds_dwordx4 v176, s[90:91]
	s_add_i32 m0, s28, 0x2000
	s_add_u32 s26, s26, 0x100080
	s_addc_u32 s27, s27, 0
	s_add_i32 s28, s80, s30
	global_load_lds_dwordx4 v128, s[90:91]
	s_mov_b32 m0, s28
	s_nop 0
	global_load_lds_dwordx4 v176, s[26:27]
	s_add_i32 m0, s28, 0x2000
	s_nop 0
	global_load_lds_dwordx4 v128, s[26:27]
	s_waitcnt vmcnt(6)
	s_waitcnt lgkmcnt(0)
	s_barrier
	s_setprio 1
	s_waitcnt lgkmcnt(0)
	v_mfma_f32_16x16x32_bf16 v[60:63], v[138:141], v[172:175], v[60:63]
	v_mfma_f32_16x16x32_bf16 v[56:59], v[148:151], v[172:175], v[56:59]
	v_mfma_f32_16x16x32_bf16 v[44:47], v[138:141], v[192:195], v[44:47]
	v_mfma_f32_16x16x32_bf16 v[40:43], v[148:151], v[192:195], v[40:43]
	v_mfma_f32_16x16x32_bf16 v[28:31], v[138:141], v[200:203], v[28:31]
	v_mfma_f32_16x16x32_bf16 v[24:27], v[148:151], v[200:203], v[24:27]
	v_mfma_f32_16x16x32_bf16 v[12:15], v[138:141], v[208:211], v[12:15]
	v_mfma_f32_16x16x32_bf16 v[8:11], v[148:151], v[208:211], v[8:11]
	v_mfma_f32_16x16x32_bf16 v[60:63], v[144:147], v[188:191], v[60:63]
	v_mfma_f32_16x16x32_bf16 v[56:59], v[152:155], v[188:191], v[56:59]
	v_mfma_f32_16x16x32_bf16 v[44:47], v[144:147], v[196:199], v[44:47]
	v_mfma_f32_16x16x32_bf16 v[40:43], v[152:155], v[196:199], v[40:43]
	v_mfma_f32_16x16x32_bf16 v[28:31], v[144:147], v[204:207], v[28:31]
	v_mfma_f32_16x16x32_bf16 v[24:27], v[152:155], v[204:207], v[24:27]
	v_mfma_f32_16x16x32_bf16 v[12:15], v[144:147], v[212:215], v[12:15]
	v_mfma_f32_16x16x32_bf16 v[8:11], v[152:155], v[212:215], v[8:11]
	s_setprio 0
	s_setprio 1
	v_mfma_f32_16x16x32_bf16 v[52:55], v[156:159], v[172:175], v[52:55]
	v_mfma_f32_16x16x32_bf16 v[48:51], v[164:167], v[172:175], v[48:51]
	v_mfma_f32_16x16x32_bf16 v[36:39], v[156:159], v[192:195], v[36:39]
	v_mfma_f32_16x16x32_bf16 v[32:35], v[164:167], v[192:195], v[32:35]
	v_mfma_f32_16x16x32_bf16 v[20:23], v[156:159], v[200:203], v[20:23]
	v_mfma_f32_16x16x32_bf16 v[16:19], v[164:167], v[200:203], v[16:19]
	v_mfma_f32_16x16x32_bf16 v[4:7], v[156:159], v[208:211], v[4:7]
	v_mfma_f32_16x16x32_bf16 v[0:3], v[164:167], v[208:211], v[0:3]
	v_mfma_f32_16x16x32_bf16 v[52:55], v[160:163], v[188:191], v[52:55]
	v_mfma_f32_16x16x32_bf16 v[48:51], v[168:171], v[188:191], v[48:51]
	v_mfma_f32_16x16x32_bf16 v[36:39], v[160:163], v[196:199], v[36:39]
	v_mfma_f32_16x16x32_bf16 v[32:35], v[168:171], v[196:199], v[32:35]
	v_mfma_f32_16x16x32_bf16 v[20:23], v[160:163], v[204:207], v[20:23]
	v_mfma_f32_16x16x32_bf16 v[16:19], v[168:171], v[204:207], v[16:19]
	s_setprio 2
	s_barrier
	v_mfma_f32_16x16x32_bf16 v[4:7], v[160:163], v[212:215], v[4:7]
	v_mfma_f32_16x16x32_bf16 v[0:3], v[168:171], v[212:215], v[0:3]
	s_setprio 0
	s_add_i32 s79, s79, 2
	s_add_u32 s24, s24, 0x100
	s_addc_u32 s25, s25, 0
	s_add_u32 s57, s57, 0x100
	s_addc_u32 s78, s78, 0
	s_cmp_gt_u32 s79, 61
	s_cbranch_scc0 .LBB0_687
	s_and_b64 vcc, exec, s[4:5]
	s_cbranch_vccz .LBB0_690
	s_barrier

.LBB0_761:
	s_add_u32 s34, s30, 0xfffc0080
	s_addc_u32 s35, s31, -1
	s_add_i32 s38, 0, 0x10000
	s_cmp_eq_u32 s79, 12
	s_cselect_b32 s49, s27, s35
	s_cselect_b32 s48, s26, s34
	v_add_u32_e32 v142, s38, v144
	s_cselect_b32 s35, s29, s78
	s_cselect_b32 s34, s28, s55
	s_add_i32 s39, 0, 0x14000
	ds_read_b128 v[138:141], v142
	ds_read_b128 v[146:149], v142 offset:1024
	ds_read_b128 v[150:153], v142 offset:2048
	ds_read_b128 v[154:157], v142 offset:3072
	v_add_u32_e32 v142, s39, v144
	ds_read_b128 v[158:161], v142
	ds_read_b128 v[162:165], v142 offset:1024
	ds_read_b128 v[166:169], v142 offset:2048
	ds_read_b128 v[170:173], v142 offset:3072
	s_add_u32 s98, s30, 0xfffc0000
	s_addc_u32 s99, s31, -1
	s_mov_b32 m0, s93
	s_nop 0
	global_load_lds_dwordx4 v128, s[98:99]
	s_mov_b32 m0, s85
	s_nop 0
	global_load_lds_dwordx4 v130, s[98:99]
	s_add_i32 m0, s10, 0xc000
	ds_read_b128 v[178:181], v145
	ds_read_b128 v[182:185], v145 offset:1024
	ds_read_b128 v[188:191], v145 offset:2048
	ds_read_b128 v[192:195], v145 offset:3072
	ds_read_b128 v[196:199], v145 offset:4096
	ds_read_b128 v[200:203], v145 offset:5120
	ds_read_b128 v[204:207], v145 offset:6144
	ds_read_b128 v[208:211], v145 offset:7168
	global_load_lds_dwordx4 v134, s[30:31]
	s_add_i32 m0, s10, 0xe000
	s_nop 0
	global_load_lds_dwordx4 v136, s[30:31]
	s_waitcnt vmcnt(8)
	s_waitcnt lgkmcnt(0)
	s_barrier
	s_setprio 1
	s_waitcnt lgkmcnt(0)
	v_mfma_f32_16x16x32_bf16 v[124:127], v[138:141], v[178:181], v[124:127]
	v_mfma_f32_16x16x32_bf16 v[112:115], v[150:153], v[178:181], v[112:115]
	v_mfma_f32_16x16x32_bf16 v[108:111], v[138:141], v[188:191], v[108:111]
	v_mfma_f32_16x16x32_bf16 v[96:99], v[150:153], v[188:191], v[96:99]
	v_mfma_f32_16x16x32_bf16 v[92:95], v[138:141], v[196:199], v[92:95]
	v_mfma_f32_16x16x32_bf16 v[80:83], v[150:153], v[196:199], v[80:83]
	v_mfma_f32_16x16x32_bf16 v[76:79], v[138:141], v[204:207], v[76:79]
	v_mfma_f32_16x16x32_bf16 v[64:67], v[150:153], v[204:207], v[64:67]
	v_mfma_f32_16x16x32_bf16 v[124:127], v[146:149], v[182:185], v[124:127]
	v_mfma_f32_16x16x32_bf16 v[112:115], v[154:157], v[182:185], v[112:115]
	v_mfma_f32_16x16x32_bf16 v[108:111], v[146:149], v[192:195], v[108:111]
	v_mfma_f32_16x16x32_bf16 v[96:99], v[154:157], v[192:195], v[96:99]
	v_mfma_f32_16x16x32_bf16 v[92:95], v[146:149], v[200:203], v[92:95]
	v_mfma_f32_16x16x32_bf16 v[80:83], v[154:157], v[200:203], v[80:83]
	v_mfma_f32_16x16x32_bf16 v[76:79], v[146:149], v[208:211], v[76:79]
	v_mfma_f32_16x16x32_bf16 v[64:67], v[154:157], v[208:211], v[64:67]
	s_setprio 0
	s_setprio 1
	v_mfma_f32_16x16x32_bf16 v[120:123], v[158:161], v[178:181], v[120:123]
	v_mfma_f32_16x16x32_bf16 v[116:119], v[166:169], v[178:181], v[116:119]
	v_mfma_f32_16x16x32_bf16 v[104:107], v[158:161], v[188:191], v[104:107]
	v_mfma_f32_16x16x32_bf16 v[100:103], v[166:169], v[188:191], v[100:103]
	v_mfma_f32_16x16x32_bf16 v[88:91], v[158:161], v[196:199], v[88:91]
	v_mfma_f32_16x16x32_bf16 v[84:87], v[166:169], v[196:199], v[84:87]
	v_mfma_f32_16x16x32_bf16 v[72:75], v[158:161], v[204:207], v[72:75]
	v_mfma_f32_16x16x32_bf16 v[68:71], v[166:169], v[204:207], v[68:71]
	v_mfma_f32_16x16x32_bf16 v[120:123], v[162:165], v[182:185], v[120:123]
	v_mfma_f32_16x16x32_bf16 v[116:119], v[170:173], v[182:185], v[116:119]
	v_mfma_f32_16x16x32_bf16 v[104:107], v[162:165], v[192:195], v[104:107]
	v_mfma_f32_16x16x32_bf16 v[100:103], v[170:173], v[192:195], v[100:103]
	v_mfma_f32_16x16x32_bf16 v[88:91], v[162:165], v[200:203], v[88:91]
	v_mfma_f32_16x16x32_bf16 v[84:87], v[170:173], v[200:203], v[84:87]
	s_setprio 2
	s_barrier
	v_mfma_f32_16x16x32_bf16 v[72:75], v[162:165], v[208:211], v[72:75]
	v_mfma_f32_16x16x32_bf16 v[68:71], v[170:173], v[208:211], v[68:71]
	s_setprio 0
	s_add_i32 s38, s38, s44
	s_add_u32 s90, s34, 0x80
	s_addc_u32 s91, s35, 0
	s_mov_b32 m0, s38
	ds_read_b128 v[178:181], v145 offset:16384
	ds_read_b128 v[182:185], v145 offset:17408
	ds_read_b128 v[188:191], v145 offset:18432
	ds_read_b128 v[192:195], v145 offset:19456
	ds_read_b128 v[196:199], v145 offset:20480
	ds_read_b128 v[200:203], v145 offset:21504
	ds_read_b128 v[204:207], v145 offset:22528
	ds_read_b128 v[208:211], v145 offset:23552
	global_load_lds_dwordx4 v176, s[34:35]
	s_add_i32 m0, s38, 0x2000
	s_add_u32 s80, s34, 0x40000
	s_addc_u32 s81, s35, 0
	s_add_i32 s38, s39, s44
	global_load_lds_dwordx4 v132, s[34:35]
	s_mov_b32 m0, s38
	s_nop 0
	global_load_lds_dwordx4 v176, s[80:81]
	s_add_i32 m0, s38, 0x2000
	s_nop 0
	global_load_lds_dwordx4 v132, s[80:81]
	s_waitcnt vmcnt(6)
	s_waitcnt lgkmcnt(0)
	s_barrier
	s_setprio 1
	s_waitcnt lgkmcnt(0)
	v_mfma_f32_16x16x32_bf16 v[60:63], v[138:141], v[178:181], v[60:63]
	v_mfma_f32_16x16x32_bf16 v[48:51], v[150:153], v[178:181], v[48:51]
	v_mfma_f32_16x16x32_bf16 v[44:47], v[138:141], v[188:191], v[44:47]
	v_mfma_f32_16x16x32_bf16 v[32:35], v[150:153], v[188:191], v[32:35]
	v_mfma_f32_16x16x32_bf16 v[28:31], v[138:141], v[196:199], v[28:31]
	v_mfma_f32_16x16x32_bf16 v[16:19], v[150:153], v[196:199], v[16:19]
	v_mfma_f32_16x16x32_bf16 v[12:15], v[138:141], v[204:207], v[12:15]
	v_mfma_f32_16x16x32_bf16 v[8:11], v[150:153], v[204:207], v[8:11]
	v_mfma_f32_16x16x32_bf16 v[60:63], v[146:149], v[182:185], v[60:63]
	v_mfma_f32_16x16x32_bf16 v[48:51], v[154:157], v[182:185], v[48:51]
	v_mfma_f32_16x16x32_bf16 v[44:47], v[146:149], v[192:195], v[44:47]
	v_mfma_f32_16x16x32_bf16 v[32:35], v[154:157], v[192:195], v[32:35]
	v_mfma_f32_16x16x32_bf16 v[28:31], v[146:149], v[200:203], v[28:31]
	v_mfma_f32_16x16x32_bf16 v[16:19], v[154:157], v[200:203], v[16:19]
	v_mfma_f32_16x16x32_bf16 v[12:15], v[146:149], v[208:211], v[12:15]
	v_mfma_f32_16x16x32_bf16 v[8:11], v[154:157], v[208:211], v[8:11]
	s_setprio 0
	s_setprio 1
	v_mfma_f32_16x16x32_bf16 v[56:59], v[158:161], v[178:181], v[56:59]
	v_mfma_f32_16x16x32_bf16 v[52:55], v[166:169], v[178:181], v[52:55]
	v_mfma_f32_16x16x32_bf16 v[40:43], v[158:161], v[188:191], v[40:43]
	v_mfma_f32_16x16x32_bf16 v[36:39], v[166:169], v[188:191], v[36:39]
	v_mfma_f32_16x16x32_bf16 v[24:27], v[158:161], v[196:199], v[24:27]
	v_mfma_f32_16x16x32_bf16 v[20:23], v[166:169], v[196:199], v[20:23]
	v_mfma_f32_16x16x32_bf16 v[4:7], v[158:161], v[204:207], v[4:7]
	v_mfma_f32_16x16x32_bf16 v[0:3], v[166:169], v[204:207], v[0:3]
	v_mfma_f32_16x16x32_bf16 v[56:59], v[162:165], v[182:185], v[56:59]
	v_mfma_f32_16x16x32_bf16 v[52:55], v[170:173], v[182:185], v[52:55]
	v_mfma_f32_16x16x32_bf16 v[40:43], v[162:165], v[192:195], v[40:43]
	v_mfma_f32_16x16x32_bf16 v[36:39], v[170:173], v[192:195], v[36:39]
	v_mfma_f32_16x16x32_bf16 v[24:27], v[162:165], v[200:203], v[24:27]
	v_mfma_f32_16x16x32_bf16 v[20:23], v[170:173], v[200:203], v[20:23]
	s_setprio 2
	s_barrier
	v_mfma_f32_16x16x32_bf16 v[4:7], v[162:165], v[208:211], v[4:7]
	v_mfma_f32_16x16x32_bf16 v[0:3], v[170:173], v[208:211], v[0:3]
	s_setprio 0
	s_add_i32 s38, 0, 0x18000
	s_add_i32 s39, 0, 0x1c000
	v_add_u32_e32 v154, s38, v144
	v_add_u32_e32 v170, s39, v144
	ds_read_b128 v[138:141], v154
	ds_read_b128 v[146:149], v154 offset:1024
	ds_read_b128 v[150:153], v154 offset:2048
	ds_read_b128 v[154:157], v154 offset:3072
	ds_read_b128 v[158:161], v170
	ds_read_b128 v[162:165], v170 offset:1024
	ds_read_b128 v[166:169], v170 offset:2048
	ds_read_b128 v[170:173], v170 offset:3072
	s_mov_b32 m0, s10
	s_nop 0
	global_load_lds_dwordx4 v128, s[48:49]
	s_mov_b32 m0, s11
	s_nop 0
	global_load_lds_dwordx4 v130, s[48:49]
	s_add_u32 s48, s48, 0x40000
	s_addc_u32 s49, s49, 0
	s_mov_b32 m0, s8
	ds_read_b128 v[178:181], v145 offset:32768
	ds_read_b128 v[182:185], v145 offset:33792
	ds_read_b128 v[188:191], v145 offset:34816
	ds_read_b128 v[192:195], v145 offset:35840
	ds_read_b128 v[196:199], v145 offset:36864
	ds_read_b128 v[200:203], v145 offset:37888
	ds_read_b128 v[204:207], v145 offset:38912
	ds_read_b128 v[208:211], v145 offset:39936
	global_load_lds_dwordx4 v128, s[48:49]
	s_mov_b32 m0, s9
	s_nop 0
	global_load_lds_dwordx4 v130, s[48:49]
	s_waitcnt vmcnt(8)
	s_waitcnt lgkmcnt(0)
	s_barrier
	s_setprio 1
	s_waitcnt lgkmcnt(0)
	v_mfma_f32_16x16x32_bf16 v[124:127], v[138:141], v[178:181], v[124:127]
	v_mfma_f32_16x16x32_bf16 v[112:115], v[150:153], v[178:181], v[112:115]
	v_mfma_f32_16x16x32_bf16 v[108:111], v[138:141], v[188:191], v[108:111]
	v_mfma_f32_16x16x32_bf16 v[96:99], v[150:153], v[188:191], v[96:99]
	v_mfma_f32_16x16x32_bf16 v[92:95], v[138:141], v[196:199], v[92:95]
	v_mfma_f32_16x16x32_bf16 v[80:83], v[150:153], v[196:199], v[80:83]
	v_mfma_f32_16x16x32_bf16 v[76:79], v[138:141], v[204:207], v[76:79]
	v_mfma_f32_16x16x32_bf16 v[64:67], v[150:153], v[204:207], v[64:67]
	v_mfma_f32_16x16x32_bf16 v[124:127], v[146:149], v[182:185], v[124:127]
	v_mfma_f32_16x16x32_bf16 v[112:115], v[154:157], v[182:185], v[112:115]
	v_mfma_f32_16x16x32_bf16 v[108:111], v[146:149], v[192:195], v[108:111]
	v_mfma_f32_16x16x32_bf16 v[96:99], v[154:157], v[192:195], v[96:99]
	v_mfma_f32_16x16x32_bf16 v[92:95], v[146:149], v[200:203], v[92:95]
	v_mfma_f32_16x16x32_bf16 v[80:83], v[154:157], v[200:203], v[80:83]
	v_mfma_f32_16x16x32_bf16 v[76:79], v[146:149], v[208:211], v[76:79]
	v_mfma_f32_16x16x32_bf16 v[64:67], v[154:157], v[208:211], v[64:67]
	s_setprio 0
	s_setprio 1
	v_mfma_f32_16x16x32_bf16 v[120:123], v[158:161], v[178:181], v[120:123]
	v_mfma_f32_16x16x32_bf16 v[116:119], v[166:169], v[178:181], v[116:119]
	v_mfma_f32_16x16x32_bf16 v[104:107], v[158:161], v[188:191], v[104:107]
	v_mfma_f32_16x16x32_bf16 v[100:103], v[166:169], v[188:191], v[100:103]
	v_mfma_f32_16x16x32_bf16 v[88:91], v[158:161], v[196:199], v[88:91]
	v_mfma_f32_16x16x32_bf16 v[84:87], v[166:169], v[196:199], v[84:87]
	v_mfma_f32_16x16x32_bf16 v[72:75], v[158:161], v[204:207], v[72:75]
	v_mfma_f32_16x16x32_bf16 v[68:71], v[166:169], v[204:207], v[68:71]
	v_mfma_f32_16x16x32_bf16 v[120:123], v[162:165], v[182:185], v[120:123]
	v_mfma_f32_16x16x32_bf16 v[116:119], v[170:173], v[182:185], v[116:119]
	v_mfma_f32_16x16x32_bf16 v[104:107], v[162:165], v[192:195], v[104:107]
	v_mfma_f32_16x16x32_bf16 v[100:103], v[170:173], v[192:195], v[100:103]
	v_mfma_f32_16x16x32_bf16 v[88:91], v[162:165], v[200:203], v[88:91]
	v_mfma_f32_16x16x32_bf16 v[84:87], v[170:173], v[200:203], v[84:87]
	s_setprio 2
	s_barrier
	v_mfma_f32_16x16x32_bf16 v[72:75], v[162:165], v[208:211], v[72:75]
	v_mfma_f32_16x16x32_bf16 v[68:71], v[170:173], v[208:211], v[68:71]
	s_setprio 0
	s_add_i32 s38, s38, s44
	s_mov_b32 m0, s38
	ds_read_b128 v[178:181], v145 offset:49152
	ds_read_b128 v[182:185], v145 offset:50176
	ds_read_b128 v[188:191], v145 offset:51200
	ds_read_b128 v[192:195], v145 offset:52224
	ds_read_b128 v[196:199], v145 offset:53248
	ds_read_b128 v[200:203], v145 offset:54272
	ds_read_b128 v[204:207], v145 offset:55296
	ds_read_b128 v[208:211], v145 offset:56320
	global_load_lds_dwordx4 v176, s[90:91]
	s_add_i32 m0, s38, 0x2000
	s_add_u32 s34, s34, 0x40080
	s_addc_u32 s35, s35, 0
	s_add_i32 s38, s39, s44
	global_load_lds_dwordx4 v132, s[90:91]
	s_mov_b32 m0, s38
	s_nop 0
	global_load_lds_dwordx4 v176, s[34:35]
	s_add_i32 m0, s38, 0x2000
	s_nop 0
	global_load_lds_dwordx4 v132, s[34:35]
	s_waitcnt vmcnt(6)
	s_waitcnt lgkmcnt(0)
	s_barrier
	s_setprio 1
	s_waitcnt lgkmcnt(0)
	v_mfma_f32_16x16x32_bf16 v[60:63], v[138:141], v[178:181], v[60:63]
	v_mfma_f32_16x16x32_bf16 v[48:51], v[150:153], v[178:181], v[48:51]
	v_mfma_f32_16x16x32_bf16 v[44:47], v[138:141], v[188:191], v[44:47]
	v_mfma_f32_16x16x32_bf16 v[32:35], v[150:153], v[188:191], v[32:35]
	v_mfma_f32_16x16x32_bf16 v[28:31], v[138:141], v[196:199], v[28:31]
	v_mfma_f32_16x16x32_bf16 v[16:19], v[150:153], v[196:199], v[16:19]
	v_mfma_f32_16x16x32_bf16 v[12:15], v[138:141], v[204:207], v[12:15]
	v_mfma_f32_16x16x32_bf16 v[8:11], v[150:153], v[204:207], v[8:11]
	v_mfma_f32_16x16x32_bf16 v[60:63], v[146:149], v[182:185], v[60:63]
	v_mfma_f32_16x16x32_bf16 v[48:51], v[154:157], v[182:185], v[48:51]
	v_mfma_f32_16x16x32_bf16 v[44:47], v[146:149], v[192:195], v[44:47]
	v_mfma_f32_16x16x32_bf16 v[32:35], v[154:157], v[192:195], v[32:35]
	v_mfma_f32_16x16x32_bf16 v[28:31], v[146:149], v[200:203], v[28:31]
	v_mfma_f32_16x16x32_bf16 v[16:19], v[154:157], v[200:203], v[16:19]
	v_mfma_f32_16x16x32_bf16 v[12:15], v[146:149], v[208:211], v[12:15]
	v_mfma_f32_16x16x32_bf16 v[8:11], v[154:157], v[208:211], v[8:11]
	s_setprio 0
	s_setprio 1
	v_mfma_f32_16x16x32_bf16 v[56:59], v[158:161], v[178:181], v[56:59]
	v_mfma_f32_16x16x32_bf16 v[52:55], v[166:169], v[178:181], v[52:55]
	v_mfma_f32_16x16x32_bf16 v[40:43], v[158:161], v[188:191], v[40:43]
	v_mfma_f32_16x16x32_bf16 v[36:39], v[166:169], v[188:191], v[36:39]
	v_mfma_f32_16x16x32_bf16 v[24:27], v[158:161], v[196:199], v[24:27]
	v_mfma_f32_16x16x32_bf16 v[20:23], v[166:169], v[196:199], v[20:23]
	v_mfma_f32_16x16x32_bf16 v[4:7], v[158:161], v[204:207], v[4:7]
	v_mfma_f32_16x16x32_bf16 v[0:3], v[166:169], v[204:207], v[0:3]
	v_mfma_f32_16x16x32_bf16 v[56:59], v[162:165], v[182:185], v[56:59]
	v_mfma_f32_16x16x32_bf16 v[52:55], v[170:173], v[182:185], v[52:55]
	v_mfma_f32_16x16x32_bf16 v[40:43], v[162:165], v[192:195], v[40:43]
	v_mfma_f32_16x16x32_bf16 v[36:39], v[170:173], v[192:195], v[36:39]
	v_mfma_f32_16x16x32_bf16 v[24:27], v[162:165], v[200:203], v[24:27]
	v_mfma_f32_16x16x32_bf16 v[20:23], v[170:173], v[200:203], v[20:23]
	s_setprio 2
	s_barrier
	v_mfma_f32_16x16x32_bf16 v[4:7], v[162:165], v[208:211], v[4:7]
	v_mfma_f32_16x16x32_bf16 v[0:3], v[170:173], v[208:211], v[0:3]
	s_setprio 0
	s_add_i32 s79, s79, 2
	s_add_u32 s30, s30, 0x100
	s_addc_u32 s31, s31, 0
	s_add_u32 s55, s55, 0x100
	s_addc_u32 s78, s78, 0
	s_cmp_gt_u32 s79, 13
	s_cbranch_scc0 .LBB0_761
	s_and_b64 vcc, exec, s[18:19]
	s_cbranch_vccz .LBB0_764
	s_barrier

.LBB0_921:
	s_add_u32 s24, s22, 0xfff00080
	s_addc_u32 s25, s23, -1
	s_add_i32 s38, 0, 0x10000
	s_cmp_eq_u32 s79, 60
	s_cselect_b32 s27, s19, s25
	s_cselect_b32 s26, s18, s24
	s_cselect_b32 s25, s21, s78
	s_cselect_b32 s24, s20, s55
	s_add_i32 s39, 0, 0x14000
	v_add_u32_e32 v140, s38, v160
	v_add_u32_e32 v158, s39, v160
	ds_read_b128 v[120:123], v140
	ds_read_b128 v[132:135], v140 offset:1024
	ds_read_b128 v[136:139], v140 offset:2048
	ds_read_b128 v[140:143], v140 offset:3072
	ds_read_b128 v[154:157], v158
	ds_read_b128 v[162:165], v158 offset:1024
	ds_read_b128 v[166:169], v158 offset:2048
	ds_read_b128 v[170:173], v158 offset:3072
	s_add_u32 s96, s22, 0xfff00000
	s_addc_u32 s97, s23, -1
	s_mov_b32 m0, s49
	s_nop 0
	global_load_lds_dwordx4 v144, s[96:97]
	s_mov_b32 m0, s50
	s_nop 0
	global_load_lds_dwordx4 v146, s[96:97]
	s_add_i32 m0, s34, 0xc000
	ds_read_b128 v[178:181], v161
	ds_read_b128 v[182:185], v161 offset:1024
	ds_read_b128 v[188:191], v161 offset:2048
	ds_read_b128 v[192:195], v161 offset:3072
	ds_read_b128 v[196:199], v161 offset:4096
	ds_read_b128 v[200:203], v161 offset:5120
	ds_read_b128 v[204:207], v161 offset:6144
	ds_read_b128 v[208:211], v161 offset:7168
	global_load_lds_dwordx4 v150, s[22:23]
	s_add_i32 m0, s34, 0xe000
	s_nop 0
	global_load_lds_dwordx4 v152, s[22:23]
	s_waitcnt vmcnt(8)
	s_waitcnt lgkmcnt(0)
	s_barrier
	s_setprio 1
	s_waitcnt lgkmcnt(0)
	v_mfma_f32_16x16x32_bf16 v[128:131], v[120:123], v[178:181], v[128:131]
	v_mfma_f32_16x16x32_bf16 v[124:127], v[136:139], v[178:181], v[124:127]
	v_mfma_f32_16x16x32_bf16 v[108:111], v[120:123], v[188:191], v[108:111]
	v_mfma_f32_16x16x32_bf16 v[104:107], v[136:139], v[188:191], v[104:107]
	v_mfma_f32_16x16x32_bf16 v[92:95], v[120:123], v[196:199], v[92:95]
	v_mfma_f32_16x16x32_bf16 v[88:91], v[136:139], v[196:199], v[88:91]
	v_mfma_f32_16x16x32_bf16 v[76:79], v[120:123], v[204:207], v[76:79]
	v_mfma_f32_16x16x32_bf16 v[72:75], v[136:139], v[204:207], v[72:75]
	v_mfma_f32_16x16x32_bf16 v[128:131], v[132:135], v[182:185], v[128:131]
	v_mfma_f32_16x16x32_bf16 v[124:127], v[140:143], v[182:185], v[124:127]
	v_mfma_f32_16x16x32_bf16 v[108:111], v[132:135], v[192:195], v[108:111]
	v_mfma_f32_16x16x32_bf16 v[104:107], v[140:143], v[192:195], v[104:107]
	v_mfma_f32_16x16x32_bf16 v[92:95], v[132:135], v[200:203], v[92:95]
	v_mfma_f32_16x16x32_bf16 v[88:91], v[140:143], v[200:203], v[88:91]
	v_mfma_f32_16x16x32_bf16 v[76:79], v[132:135], v[208:211], v[76:79]
	v_mfma_f32_16x16x32_bf16 v[72:75], v[140:143], v[208:211], v[72:75]
	s_setprio 0
	s_setprio 1
	v_mfma_f32_16x16x32_bf16 v[116:119], v[154:157], v[178:181], v[116:119]
	v_mfma_f32_16x16x32_bf16 v[112:115], v[166:169], v[178:181], v[112:115]
	v_mfma_f32_16x16x32_bf16 v[100:103], v[154:157], v[188:191], v[100:103]
	v_mfma_f32_16x16x32_bf16 v[96:99], v[166:169], v[188:191], v[96:99]
	v_mfma_f32_16x16x32_bf16 v[84:87], v[154:157], v[196:199], v[84:87]
	v_mfma_f32_16x16x32_bf16 v[80:83], v[166:169], v[196:199], v[80:83]
	v_mfma_f32_16x16x32_bf16 v[68:71], v[154:157], v[204:207], v[68:71]
	v_mfma_f32_16x16x32_bf16 v[64:67], v[166:169], v[204:207], v[64:67]
	v_mfma_f32_16x16x32_bf16 v[116:119], v[162:165], v[182:185], v[116:119]
	v_mfma_f32_16x16x32_bf16 v[112:115], v[170:173], v[182:185], v[112:115]
	v_mfma_f32_16x16x32_bf16 v[100:103], v[162:165], v[192:195], v[100:103]
	v_mfma_f32_16x16x32_bf16 v[96:99], v[170:173], v[192:195], v[96:99]
	v_mfma_f32_16x16x32_bf16 v[84:87], v[162:165], v[200:203], v[84:87]
	v_mfma_f32_16x16x32_bf16 v[80:83], v[170:173], v[200:203], v[80:83]
	s_setprio 2
	s_barrier
	v_mfma_f32_16x16x32_bf16 v[68:71], v[162:165], v[208:211], v[68:71]
	v_mfma_f32_16x16x32_bf16 v[64:67], v[170:173], v[208:211], v[64:67]
	s_setprio 0
	s_add_i32 s38, s38, s31
	s_add_u32 s90, s24, 0x80
	s_addc_u32 s91, s25, 0
	s_mov_b32 m0, s38
	ds_read_b128 v[178:181], v161 offset:16384
	ds_read_b128 v[182:185], v161 offset:17408
	ds_read_b128 v[188:191], v161 offset:18432
	ds_read_b128 v[192:195], v161 offset:19456
	ds_read_b128 v[196:199], v161 offset:20480
	ds_read_b128 v[200:203], v161 offset:21504
	ds_read_b128 v[204:207], v161 offset:22528
	ds_read_b128 v[208:211], v161 offset:23552
	global_load_lds_dwordx4 v176, s[24:25]
	s_add_i32 m0, s38, 0x2000
	s_add_u32 s80, s24, 0x100000
	s_addc_u32 s81, s25, 0
	s_add_i32 s38, s39, s31
	global_load_lds_dwordx4 v148, s[24:25]
	s_mov_b32 m0, s38
	s_nop 0
	global_load_lds_dwordx4 v176, s[80:81]
	s_add_i32 m0, s38, 0x2000
	s_nop 0
	global_load_lds_dwordx4 v148, s[80:81]
	s_waitcnt vmcnt(6)
	s_waitcnt lgkmcnt(0)
	s_barrier
	s_setprio 1
	s_waitcnt lgkmcnt(0)
	v_mfma_f32_16x16x32_bf16 v[60:63], v[120:123], v[178:181], v[60:63]
	v_mfma_f32_16x16x32_bf16 v[56:59], v[136:139], v[178:181], v[56:59]
	v_mfma_f32_16x16x32_bf16 v[48:51], v[120:123], v[188:191], v[48:51]
	v_mfma_f32_16x16x32_bf16 v[40:43], v[136:139], v[188:191], v[40:43]
	v_mfma_f32_16x16x32_bf16 v[32:35], v[120:123], v[196:199], v[32:35]
	v_mfma_f32_16x16x32_bf16 v[24:27], v[136:139], v[196:199], v[24:27]
	v_mfma_f32_16x16x32_bf16 v[16:19], v[120:123], v[204:207], v[16:19]
	v_mfma_f32_16x16x32_bf16 v[8:11], v[136:139], v[204:207], v[8:11]
	v_mfma_f32_16x16x32_bf16 v[60:63], v[132:135], v[182:185], v[60:63]
	v_mfma_f32_16x16x32_bf16 v[56:59], v[140:143], v[182:185], v[56:59]
	v_mfma_f32_16x16x32_bf16 v[48:51], v[132:135], v[192:195], v[48:51]
	v_mfma_f32_16x16x32_bf16 v[40:43], v[140:143], v[192:195], v[40:43]
	v_mfma_f32_16x16x32_bf16 v[32:35], v[132:135], v[200:203], v[32:35]
	v_mfma_f32_16x16x32_bf16 v[24:27], v[140:143], v[200:203], v[24:27]
	v_mfma_f32_16x16x32_bf16 v[16:19], v[132:135], v[208:211], v[16:19]
	v_mfma_f32_16x16x32_bf16 v[8:11], v[140:143], v[208:211], v[8:11]
	s_setprio 0
	s_setprio 1
	v_mfma_f32_16x16x32_bf16 v[52:55], v[154:157], v[178:181], v[52:55]
	v_mfma_f32_16x16x32_bf16 v[44:47], v[166:169], v[178:181], v[44:47]
	v_mfma_f32_16x16x32_bf16 v[36:39], v[154:157], v[188:191], v[36:39]
	v_mfma_f32_16x16x32_bf16 v[28:31], v[166:169], v[188:191], v[28:31]
	v_mfma_f32_16x16x32_bf16 v[20:23], v[154:157], v[196:199], v[20:23]
	v_mfma_f32_16x16x32_bf16 v[12:15], v[166:169], v[196:199], v[12:15]
	v_mfma_f32_16x16x32_bf16 v[4:7], v[154:157], v[204:207], v[4:7]
	v_mfma_f32_16x16x32_bf16 v[0:3], v[166:169], v[204:207], v[0:3]
	v_mfma_f32_16x16x32_bf16 v[52:55], v[162:165], v[182:185], v[52:55]
	v_mfma_f32_16x16x32_bf16 v[44:47], v[170:173], v[182:185], v[44:47]
	v_mfma_f32_16x16x32_bf16 v[36:39], v[162:165], v[192:195], v[36:39]
	v_mfma_f32_16x16x32_bf16 v[28:31], v[170:173], v[192:195], v[28:31]
	v_mfma_f32_16x16x32_bf16 v[20:23], v[162:165], v[200:203], v[20:23]
	v_mfma_f32_16x16x32_bf16 v[12:15], v[170:173], v[200:203], v[12:15]
	s_setprio 2
	s_barrier
	v_mfma_f32_16x16x32_bf16 v[4:7], v[162:165], v[208:211], v[4:7]
	v_mfma_f32_16x16x32_bf16 v[0:3], v[170:173], v[208:211], v[0:3]
	s_setprio 0
	s_add_i32 s38, 0, 0x18000
	s_add_i32 s39, 0, 0x1c000
	v_add_u32_e32 v140, s38, v160
	v_add_u32_e32 v170, s39, v160
	ds_read_b128 v[120:123], v140
	ds_read_b128 v[132:135], v140 offset:1024
	ds_read_b128 v[136:139], v140 offset:2048
	ds_read_b128 v[140:143], v140 offset:3072
	ds_read_b128 v[154:157], v170
	ds_read_b128 v[162:165], v170 offset:1024
	ds_read_b128 v[166:169], v170 offset:2048
	ds_read_b128 v[170:173], v170 offset:3072
	s_mov_b32 m0, s34
	s_nop 0
	global_load_lds_dwordx4 v144, s[26:27]
	s_mov_b32 m0, s35
	s_nop 0
	global_load_lds_dwordx4 v146, s[26:27]
	s_add_u32 s26, s26, 0x100000
	s_addc_u32 s27, s27, 0
	s_mov_b32 m0, s36
	ds_read_b128 v[178:181], v161 offset:32768
	ds_read_b128 v[182:185], v161 offset:33792
	ds_read_b128 v[188:191], v161 offset:34816
	ds_read_b128 v[192:195], v161 offset:35840
	ds_read_b128 v[196:199], v161 offset:36864
	ds_read_b128 v[200:203], v161 offset:37888
	ds_read_b128 v[204:207], v161 offset:38912
	ds_read_b128 v[208:211], v161 offset:39936
	global_load_lds_dwordx4 v144, s[26:27]
	s_mov_b32 m0, s43
	s_nop 0
	global_load_lds_dwordx4 v146, s[26:27]
	s_waitcnt vmcnt(8)
	s_waitcnt lgkmcnt(0)
	s_barrier
	s_setprio 1
	s_waitcnt lgkmcnt(0)
	v_mfma_f32_16x16x32_bf16 v[128:131], v[120:123], v[178:181], v[128:131]
	v_mfma_f32_16x16x32_bf16 v[124:127], v[136:139], v[178:181], v[124:127]
	v_mfma_f32_16x16x32_bf16 v[108:111], v[120:123], v[188:191], v[108:111]
	v_mfma_f32_16x16x32_bf16 v[104:107], v[136:139], v[188:191], v[104:107]
	v_mfma_f32_16x16x32_bf16 v[92:95], v[120:123], v[196:199], v[92:95]
	v_mfma_f32_16x16x32_bf16 v[88:91], v[136:139], v[196:199], v[88:91]
	v_mfma_f32_16x16x32_bf16 v[76:79], v[120:123], v[204:207], v[76:79]
	v_mfma_f32_16x16x32_bf16 v[72:75], v[136:139], v[204:207], v[72:75]
	v_mfma_f32_16x16x32_bf16 v[128:131], v[132:135], v[182:185], v[128:131]
	v_mfma_f32_16x16x32_bf16 v[124:127], v[140:143], v[182:185], v[124:127]
	v_mfma_f32_16x16x32_bf16 v[108:111], v[132:135], v[192:195], v[108:111]
	v_mfma_f32_16x16x32_bf16 v[104:107], v[140:143], v[192:195], v[104:107]
	v_mfma_f32_16x16x32_bf16 v[92:95], v[132:135], v[200:203], v[92:95]
	v_mfma_f32_16x16x32_bf16 v[88:91], v[140:143], v[200:203], v[88:91]
	v_mfma_f32_16x16x32_bf16 v[76:79], v[132:135], v[208:211], v[76:79]
	v_mfma_f32_16x16x32_bf16 v[72:75], v[140:143], v[208:211], v[72:75]
	s_setprio 0
	s_setprio 1
	v_mfma_f32_16x16x32_bf16 v[116:119], v[154:157], v[178:181], v[116:119]
	v_mfma_f32_16x16x32_bf16 v[112:115], v[166:169], v[178:181], v[112:115]
	v_mfma_f32_16x16x32_bf16 v[100:103], v[154:157], v[188:191], v[100:103]
	v_mfma_f32_16x16x32_bf16 v[96:99], v[166:169], v[188:191], v[96:99]
	v_mfma_f32_16x16x32_bf16 v[84:87], v[154:157], v[196:199], v[84:87]
	v_mfma_f32_16x16x32_bf16 v[80:83], v[166:169], v[196:199], v[80:83]
	v_mfma_f32_16x16x32_bf16 v[68:71], v[154:157], v[204:207], v[68:71]
	v_mfma_f32_16x16x32_bf16 v[64:67], v[166:169], v[204:207], v[64:67]
	v_mfma_f32_16x16x32_bf16 v[116:119], v[162:165], v[182:185], v[116:119]
	v_mfma_f32_16x16x32_bf16 v[112:115], v[170:173], v[182:185], v[112:115]
	v_mfma_f32_16x16x32_bf16 v[100:103], v[162:165], v[192:195], v[100:103]
	v_mfma_f32_16x16x32_bf16 v[96:99], v[170:173], v[192:195], v[96:99]
	v_mfma_f32_16x16x32_bf16 v[84:87], v[162:165], v[200:203], v[84:87]
	v_mfma_f32_16x16x32_bf16 v[80:83], v[170:173], v[200:203], v[80:83]
	s_setprio 2
	s_barrier
	v_mfma_f32_16x16x32_bf16 v[68:71], v[162:165], v[208:211], v[68:71]
	v_mfma_f32_16x16x32_bf16 v[64:67], v[170:173], v[208:211], v[64:67]
	s_setprio 0
	s_add_i32 s26, s38, s31
	s_mov_b32 m0, s26
	ds_read_b128 v[178:181], v161 offset:49152
	ds_read_b128 v[182:185], v161 offset:50176
	ds_read_b128 v[188:191], v161 offset:51200
	ds_read_b128 v[192:195], v161 offset:52224
	ds_read_b128 v[196:199], v161 offset:53248
	ds_read_b128 v[200:203], v161 offset:54272
	ds_read_b128 v[204:207], v161 offset:55296
	ds_read_b128 v[208:211], v161 offset:56320
	global_load_lds_dwordx4 v176, s[90:91]
	s_add_i32 m0, s26, 0x2000
	s_add_u32 s24, s24, 0x100080
	s_addc_u32 s25, s25, 0
	s_add_i32 s26, s39, s31
	global_load_lds_dwordx4 v148, s[90:91]
	s_mov_b32 m0, s26
	s_nop 0
	global_load_lds_dwordx4 v176, s[24:25]
	s_add_i32 m0, s26, 0x2000
	s_nop 0
	global_load_lds_dwordx4 v148, s[24:25]
	s_waitcnt vmcnt(6)
	s_waitcnt lgkmcnt(0)
	s_barrier
	s_setprio 1
	s_waitcnt lgkmcnt(0)
	v_mfma_f32_16x16x32_bf16 v[60:63], v[120:123], v[178:181], v[60:63]
	v_mfma_f32_16x16x32_bf16 v[56:59], v[136:139], v[178:181], v[56:59]
	v_mfma_f32_16x16x32_bf16 v[48:51], v[120:123], v[188:191], v[48:51]
	v_mfma_f32_16x16x32_bf16 v[40:43], v[136:139], v[188:191], v[40:43]
	v_mfma_f32_16x16x32_bf16 v[32:35], v[120:123], v[196:199], v[32:35]
	v_mfma_f32_16x16x32_bf16 v[24:27], v[136:139], v[196:199], v[24:27]
	v_mfma_f32_16x16x32_bf16 v[16:19], v[120:123], v[204:207], v[16:19]
	v_mfma_f32_16x16x32_bf16 v[8:11], v[136:139], v[204:207], v[8:11]
	v_mfma_f32_16x16x32_bf16 v[60:63], v[132:135], v[182:185], v[60:63]
	v_mfma_f32_16x16x32_bf16 v[56:59], v[140:143], v[182:185], v[56:59]
	v_mfma_f32_16x16x32_bf16 v[48:51], v[132:135], v[192:195], v[48:51]
	v_mfma_f32_16x16x32_bf16 v[40:43], v[140:143], v[192:195], v[40:43]
	v_mfma_f32_16x16x32_bf16 v[32:35], v[132:135], v[200:203], v[32:35]
	v_mfma_f32_16x16x32_bf16 v[24:27], v[140:143], v[200:203], v[24:27]
	v_mfma_f32_16x16x32_bf16 v[16:19], v[132:135], v[208:211], v[16:19]
	v_mfma_f32_16x16x32_bf16 v[8:11], v[140:143], v[208:211], v[8:11]
	s_setprio 0
	s_setprio 1
	v_mfma_f32_16x16x32_bf16 v[52:55], v[154:157], v[178:181], v[52:55]
	v_mfma_f32_16x16x32_bf16 v[44:47], v[166:169], v[178:181], v[44:47]
	v_mfma_f32_16x16x32_bf16 v[36:39], v[154:157], v[188:191], v[36:39]
	v_mfma_f32_16x16x32_bf16 v[28:31], v[166:169], v[188:191], v[28:31]
	v_mfma_f32_16x16x32_bf16 v[20:23], v[154:157], v[196:199], v[20:23]
	v_mfma_f32_16x16x32_bf16 v[12:15], v[166:169], v[196:199], v[12:15]
	v_mfma_f32_16x16x32_bf16 v[4:7], v[154:157], v[204:207], v[4:7]
	v_mfma_f32_16x16x32_bf16 v[0:3], v[166:169], v[204:207], v[0:3]
	v_mfma_f32_16x16x32_bf16 v[52:55], v[162:165], v[182:185], v[52:55]
	v_mfma_f32_16x16x32_bf16 v[44:47], v[170:173], v[182:185], v[44:47]
	v_mfma_f32_16x16x32_bf16 v[36:39], v[162:165], v[192:195], v[36:39]
	v_mfma_f32_16x16x32_bf16 v[28:31], v[170:173], v[192:195], v[28:31]
	v_mfma_f32_16x16x32_bf16 v[20:23], v[162:165], v[200:203], v[20:23]
	v_mfma_f32_16x16x32_bf16 v[12:15], v[170:173], v[200:203], v[12:15]
	s_setprio 2
	s_barrier
	v_mfma_f32_16x16x32_bf16 v[4:7], v[162:165], v[208:211], v[4:7]
	v_mfma_f32_16x16x32_bf16 v[0:3], v[170:173], v[208:211], v[0:3]
	s_setprio 0
	s_add_i32 s79, s79, 2
	s_add_u32 s22, s22, 0x100
	s_addc_u32 s23, s23, 0
	s_add_u32 s55, s55, 0x100
	s_addc_u32 s78, s78, 0
	s_cmp_gt_u32 s79, 61
	s_cbranch_scc0 .LBB0_921
	s_and_b64 vcc, exec, s[8:9]
	s_cbranch_vccz .LBB0_924
	s_barrier
